# P6->P7 grid barrier replaced by arrival counter + deferred wait inside first P7 K loop (write-after-read seam only)
# speedup vs baseline: 1.0152x; 1.0056x over previous
.LBB0_988:
	s_waitcnt vmcnt(0)
	s_barrier
	s_and_saveexec_b64 s[10:11], s[92:93]
	s_cbranch_execz .LBB0_1040
	v_mov_b32_e32 v2, 0x2b5d008
	v_mov_b32_e32 v3, 1
	global_atomic_add v2, v3, s[88:89]
.LBB0_1040:
	s_or_b64 exec, exec, s[10:11]
	s_waitcnt lgkmcnt(0)
	v_mov_b32_e32 v2, v0
	v_mov_b32_e32 v6, v0
	s_cmpk_lt_i32 s2, 0x200
	s_barrier
	s_mov_b32 s100, 1
	s_cselect_b64 s[16:17], -1, 0
	s_cmpk_gt_i32 s2, 0x1ff
	v_readfirstlane_b32 s0, v6
	s_cbranch_scc1 .LBB0_1064
	v_bfe_i32 v3, v6, 27, 1
	v_lshlrev_b32_e32 v2, 4, v6
	v_lshrrev_b32_e32 v3, 22, v3
	v_add_u32_e32 v3, v2, v3
	v_and_b32_e32 v3, 0xfffffc00, v3
	s_load_dwordx2 s[10:11], s[96:97], 0xe8
	v_sub_u32_e32 v2, v2, v3
	v_lshrrev_b32_e32 v3, 4, v2
	v_ashrrev_i32_e32 v4, 31, v6
	v_bitop3_b32 v2, v3, v2, 32 bitop3:0x6c
	v_lshrrev_b32_e32 v4, 26, v4
	v_ashrrev_i32_e32 v3, 31, v2
	v_add_u32_e32 v4, v6, v4
	v_lshrrev_b32_e32 v3, 26, v3
	v_ashrrev_i32_e32 v8, 6, v4
	s_waitcnt lgkmcnt(0)
	s_add_u32 s3, s10, 0xae00000
	v_add_u32_e32 v3, v2, v3
	v_lshlrev_b32_e32 v4, 3, v8
	s_addc_u32 s4, s11, 0
	v_ashrrev_i32_e32 v7, 6, v3
	v_and_b32_e32 v4, -16, v4
	s_add_u32 s5, s10, 0x200000
	v_add_u32_e32 v4, v7, v4
	v_and_b32_e32 v5, 3, v7
	s_mov_b32 s8, 0x1fffe0
	s_addc_u32 s6, s11, 0
	v_and_or_b32 v5, v4, s8, v5
	s_ashr_i32 s8, s2, 31
	s_lshr_b32 s9, s8, 29
	s_add_i32 s9, s2, s9
	s_ashr_i32 s12, s9, 3
	s_and_b32 s9, s9, -8
	s_sub_i32 s9, s2, s9
	s_lshr_b32 s14, s9, 31
	s_or_b32 s14, s14, 64
	s_mul_i32 s9, s14, s9
	s_add_i32 s9, s9, s12
	s_ashr_i32 s12, s9, 31
	s_lshr_b32 s12, s12, 26
	v_lshrrev_b32_e32 v9, 2, v4
	v_lshlrev_b32_e32 v10, 1, v4
	v_and_b32_e32 v3, 0xc0, v3
	s_add_i32 s12, s9, s12
	v_and_b32_e32 v9, 4, v9
	v_and_b32_e32 v10, 24, v10
	v_sub_u32_e32 v2, v2, v3
	v_mov_b32_e32 v3, 1
	s_ashr_i32 s12, s12, 6
	v_or3_b32 v5, v5, v9, v10
	v_lshlrev_b32_e32 v9, 5, v8
	v_ashrrev_i16_sdwa v2, v3, sext(v2) dst_sel:DWORD dst_unused:UNUSED_PAD src0_sel:DWORD src1_sel:BYTE_0
	s_lshl_b32 s18, s12, 3
	v_and_b32_e32 v10, 32, v9
	v_bfe_i32 v9, v2, 0, 16
	s_sub_i32 s14, 64, s18
	s_lshl_b32 s12, s12, 6
	v_add_lshl_u32 v2, v10, v9, 1
	s_min_u32 s19, s14, 8
	s_sub_i32 s9, s9, s12
	v_lshl_add_u32 v138, v5, 11, v2
	s_sext_i32_i8 s12, s9
	v_cvt_f32_ubyte0_e32 v5, s19
	v_cvt_f32_i32_e32 v3, s12
	v_rcp_iflag_f32_e32 v10, v5
	v_lshl_add_u32 v140, v4, 11, v2
	s_ashr_i32 s1, s0, 6
	s_ashr_i32 s12, s12, 30
	v_mul_f32_e32 v2, v3, v10
	v_trunc_f32_e32 v2, v2
	v_fma_f32 v3, -v2, v5, v3
	v_cvt_i32_f32_e32 v2, v2
	s_ashr_i32 s13, s0, 8
	s_lshl_b32 s7, s1, 10
	s_or_b32 s12, s12, 1
	v_cmp_ge_f32_e64 s[14:15], |v3|, v5
	s_and_b64 s[14:15], s[14:15], exec
	s_cselect_b32 s12, s12, 0
	v_readfirstlane_b32 s14, v2
	s_add_i32 s12, s14, s12
	s_mul_i32 s14, s12, s19
	s_sub_i32 s9, s9, s14
	s_sext_i32_i8 s9, s9
	s_add_i32 s14, s18, s9
	s_ashr_i32 s15, s14, 31
	s_lshl_b64 s[42:43], s[14:15], 19
	s_add_u32 s66, s3, s42
	s_addc_u32 s67, s4, s43
	s_bfe_i64 s[14:15], s[12:13], 0x80000
	s_lshl_b64 s[14:15], s[14:15], 19
	s_add_u32 s68, s5, s14
	s_addc_u32 s69, s6, s15
	v_mov_b32_e32 v139, 0
	s_add_i32 s9, s7, 0
	v_lshl_add_u64 v[2:3], s[68:69], 0, v[138:139]
	s_add_i32 m0, s9, 0x10000
	s_mov_b64 s[14:15], 0x20000
	global_load_lds_dwordx4 v138, s[68:69]
	v_lshl_add_u64 v[4:5], v[2:3], 0, s[14:15]
	s_add_i32 m0, s9, 0x12000
	v_mov_b32_e32 v141, v139
	global_load_lds_dwordx4 v[4:5], off
	v_lshl_add_u64 v[4:5], s[66:67], 0, v[140:141]
	s_mov_b32 m0, s9
	s_add_i32 s24, s9, 0x2000
	global_load_lds_dwordx4 v140, s[66:67]
	v_lshl_add_u64 v[10:11], v[4:5], 0, s[14:15]
	s_mov_b32 m0, s24
	s_mov_b64 s[18:19], 0x40000
	global_load_lds_dwordx4 v[10:11], off
	v_lshl_add_u64 v[10:11], v[2:3], 0, s[18:19]
	s_add_i32 m0, s9, 0x14000
	s_mov_b64 s[20:21], 0x60000
	global_load_lds_dwordx4 v[10:11], off
	v_lshl_add_u64 v[10:11], v[2:3], 0, s[20:21]
	s_add_i32 m0, s9, 0x16000
	s_add_i32 s25, s9, 0x4000
	global_load_lds_dwordx4 v[10:11], off
	v_lshl_add_u64 v[10:11], v[4:5], 0, s[18:19]
	s_mov_b32 m0, s25
	s_add_i32 s26, s9, 0x6000
	global_load_lds_dwordx4 v[10:11], off
	v_lshl_add_u64 v[10:11], v[4:5], 0, s[20:21]
	s_mov_b32 m0, s26
	s_cmp_eq_u32 s13, 1
	global_load_lds_dwordx4 v[10:11], off
	s_cselect_b64 s[22:23], -1, 0
	s_cmp_lg_u32 s13, 1
	s_mov_b32 s41, 0
	s_cbranch_scc1 .LBB0_1043
	s_barrier

.LBB0_1049:
	s_cmp_lg_u32 s100, 1
	s_cbranch_scc1 .Ldw_skip_p7
	s_cmp_lg_u32 s69, 8
	s_cbranch_scc1 .Ldw_skip_p7
	s_mov_b32 s100, 0
	s_cmp_eq_u64 s[92:93], 0
	s_cbranch_scc1 .Ldw_skip_p7
	v_mov_b32_e32 v216, 0x2b5d008
	s_mov_b32 s101, 0x100000
.Ldw_poll_p7:
	global_load_dword v217, v216, s[88:89] sc1
	s_waitcnt vmcnt(0)
	v_readfirstlane_b32 s99, v217
	s_cmp_ge_u32 s99, 0x100
	s_cbranch_scc1 .Ldw_skip_p7
	s_sleep 1
	s_sub_u32 s101, s101, 1
	s_cmp_lg_u32 s101, 0
	s_cbranch_scc1 .Ldw_poll_p7
